# P1 Toeplitz p-loop unrolled x2 (16 loads in flight)
# speedup vs baseline: 1.0009x; 1.0009x over previous
; #define INP(i) ((const float*)ld_ptr(pb, (i)))
; __global__ void __launch_bounds__(512, 2) hybrid_fwd(Params P) {
;     ...
;                 for (int p = 0; p < 64; ++p) { const float ar = ap[2 * p], ai = ap[2 * p + 1], br = bp[p * 32], bi = bp[p * 32 + 1];
;                     const float wr_ = ar * br - ai * bi, wi_ = ar * bi + ai * br; acc += cr[p] * wr_ - ci[p] * wi_; }
;                 if (tau == 0 && c == cp) acc += INP(22)[lg * 16 + c];
.LBB0_178:
	v_lshl_add_u64 v[44:45], s[6:7], 0, v[8:9]
	v_add_co_u32_e32 v54, vcc, 0x500000, v44
	v_lshl_add_u64 v[38:39], s[6:7], 0, v[6:7]
	s_nop 0
	v_addc_co_u32_e32 v55, vcc, 0, v45, vcc
	v_lshl_add_u64 v[46:47], v[26:27], 0, s[0:1]
	v_lshl_add_u64 v[48:49], v[10:11], 0, s[0:1]
	v_lshl_add_u64 v[52:53], v[38:39], 0, s[14:15]
	v_add_co_u32_e32 v38, vcc, 0x400000, v38
	global_load_dwordx4 v[30:33], v[46:47], off
	global_load_dwordx4 v[34:37], v[48:49], off
	v_addc_co_u32_e32 v39, vcc, 0, v39, vcc
	global_load_dwordx2 v[56:57], v[54:55], off
	global_load_dwordx4 v[44:47], v[52:53], off offset:16
	global_load_dwordx2 v[58:59], v[54:55], off offset:128
	global_load_dwordx2 v[60:61], v[54:55], off offset:256
	global_load_dwordx4 v[48:51], v[38:39], off
	global_load_dwordx2 v[62:63], v[54:55], off offset:384
	s_add_u32 s0, s0, 16
	s_addc_u32 s1, s1, 0
	v_lshl_add_u64 v[6:7], v[6:7], 0, 32
	v_lshl_add_u64 v[8:9], v[8:9], 0, s[16:17]
	v_lshl_add_u64 v[84:85], s[6:7], 0, v[8:9]
	v_add_co_u32_e32 v94, vcc, 0x500000, v84
	v_lshl_add_u64 v[78:79], s[6:7], 0, v[6:7]
	s_nop 0
	v_addc_co_u32_e32 v95, vcc, 0, v85, vcc
	v_lshl_add_u64 v[86:87], v[26:27], 0, s[0:1]
	v_lshl_add_u64 v[88:89], v[10:11], 0, s[0:1]
	v_lshl_add_u64 v[92:93], v[78:79], 0, s[14:15]
	v_add_co_u32_e32 v78, vcc, 0x400000, v78
	global_load_dwordx4 v[70:73], v[86:87], off
	global_load_dwordx4 v[74:77], v[88:89], off
	v_addc_co_u32_e32 v79, vcc, 0, v79, vcc
	global_load_dwordx2 v[96:97], v[94:95], off
	global_load_dwordx4 v[84:87], v[92:93], off offset:16
	global_load_dwordx2 v[98:99], v[94:95], off offset:128
	global_load_dwordx2 v[100:101], v[94:95], off offset:256
	global_load_dwordx4 v[88:91], v[78:79], off
	global_load_dwordx2 v[102:103], v[94:95], off offset:384
	s_add_u32 s0, s0, 16
	s_addc_u32 s1, s1, 0
	v_lshl_add_u64 v[6:7], v[6:7], 0, 32
	v_lshl_add_u64 v[8:9], v[8:9], 0, s[16:17]
	s_cmpk_eq_i32 s0, 0x100
	s_waitcnt vmcnt(15)
	v_mov_b32_e32 v38, v30
	s_waitcnt vmcnt(14)
	v_mov_b32_e32 v39, v34
	v_mov_b32_e32 v34, v31
	v_mov_b32_e32 v30, v32
	v_mov_b32_e32 v31, v36
	v_mov_b32_e32 v36, v33
	s_waitcnt vmcnt(10)
	v_pk_mul_f32 v[32:33], v[44:45], v[60:61] op_sel:[1,1] op_sel_hi:[0,1]
	s_waitcnt vmcnt(8)
	v_pk_mul_f32 v[52:53], v[46:47], v[62:63] op_sel:[1,1] op_sel_hi:[0,1]
	v_pk_mul_f32 v[54:55], v[48:49], v[56:57] op_sel:[1,1] op_sel_hi:[0,1]
	v_pk_mul_f32 v[64:65], v[50:51], v[58:59] op_sel:[1,1] op_sel_hi:[0,1]
	v_pk_fma_f32 v[66:67], v[44:45], v[60:61], v[32:33] neg_lo:[0,0,1] neg_hi:[0,0,1]
	v_pk_fma_f32 v[32:33], v[44:45], v[60:61], v[32:33] op_sel_hi:[1,0,1]
	v_pk_fma_f32 v[44:45], v[46:47], v[62:63], v[52:53] neg_lo:[0,0,1] neg_hi:[0,0,1]
	v_pk_fma_f32 v[46:47], v[46:47], v[62:63], v[52:53] op_sel_hi:[1,0,1]
	v_pk_fma_f32 v[52:53], v[48:49], v[56:57], v[54:55] neg_lo:[0,0,1] neg_hi:[0,0,1]
	v_pk_fma_f32 v[48:49], v[48:49], v[56:57], v[54:55] op_sel_hi:[1,0,1]
	v_pk_fma_f32 v[54:55], v[50:51], v[58:59], v[64:65] neg_lo:[0,0,1] neg_hi:[0,0,1]
	v_pk_fma_f32 v[50:51], v[50:51], v[58:59], v[64:65] op_sel_hi:[1,0,1]
	v_mov_b32_e32 v45, v47
	v_mov_b32_e32 v53, v49
	v_mov_b32_e32 v67, v33
	v_mov_b32_e32 v55, v51
	v_pk_mul_f32 v[32:33], v[36:37], v[44:45]
	v_pk_mul_f32 v[36:37], v[38:39], v[52:53]
	v_pk_mul_f32 v[34:35], v[34:35], v[54:55]
	v_sub_f32_e32 v21, v36, v37
	v_pk_mul_f32 v[30:31], v[30:31], v[66:67]
	v_sub_f32_e32 v29, v34, v35
	v_add_f32_e32 v1, v1, v21
	v_sub_f32_e32 v3, v30, v31
	v_add_f32_e32 v1, v1, v29
	v_sub_f32_e32 v5, v32, v33
	v_add_f32_e32 v1, v1, v3
	v_add_f32_e32 v1, v1, v5
	s_waitcnt vmcnt(7)
	v_mov_b32_e32 v78, v70
	s_waitcnt vmcnt(6)
	v_mov_b32_e32 v79, v74
	v_mov_b32_e32 v74, v71
	v_mov_b32_e32 v70, v72
	v_mov_b32_e32 v71, v76
	v_mov_b32_e32 v76, v73
	s_waitcnt vmcnt(2)
	v_pk_mul_f32 v[72:73], v[84:85], v[100:101] op_sel:[1,1] op_sel_hi:[0,1]
	s_waitcnt vmcnt(0)
	v_pk_mul_f32 v[92:93], v[86:87], v[102:103] op_sel:[1,1] op_sel_hi:[0,1]
	v_pk_mul_f32 v[94:95], v[88:89], v[96:97] op_sel:[1,1] op_sel_hi:[0,1]
	v_pk_mul_f32 v[104:105], v[90:91], v[98:99] op_sel:[1,1] op_sel_hi:[0,1]
	v_pk_fma_f32 v[106:107], v[84:85], v[100:101], v[72:73] neg_lo:[0,0,1] neg_hi:[0,0,1]
	v_pk_fma_f32 v[72:73], v[84:85], v[100:101], v[72:73] op_sel_hi:[1,0,1]
	v_pk_fma_f32 v[84:85], v[86:87], v[102:103], v[92:93] neg_lo:[0,0,1] neg_hi:[0,0,1]
	v_pk_fma_f32 v[86:87], v[86:87], v[102:103], v[92:93] op_sel_hi:[1,0,1]
	v_pk_fma_f32 v[92:93], v[88:89], v[96:97], v[94:95] neg_lo:[0,0,1] neg_hi:[0,0,1]
	v_pk_fma_f32 v[88:89], v[88:89], v[96:97], v[94:95] op_sel_hi:[1,0,1]
	v_pk_fma_f32 v[94:95], v[90:91], v[98:99], v[104:105] neg_lo:[0,0,1] neg_hi:[0,0,1]
	v_pk_fma_f32 v[90:91], v[90:91], v[98:99], v[104:105] op_sel_hi:[1,0,1]
	v_mov_b32_e32 v85, v87
	v_mov_b32_e32 v93, v89
	v_mov_b32_e32 v107, v73
	v_mov_b32_e32 v95, v91
	v_pk_mul_f32 v[72:73], v[76:77], v[84:85]
	v_pk_mul_f32 v[76:77], v[78:79], v[92:93]
	v_pk_mul_f32 v[74:75], v[74:75], v[94:95]
	v_sub_f32_e32 v21, v76, v77
	v_pk_mul_f32 v[70:71], v[70:71], v[106:107]
	v_sub_f32_e32 v29, v74, v75
	v_add_f32_e32 v1, v1, v21
	v_sub_f32_e32 v3, v70, v71
	v_add_f32_e32 v1, v1, v29
	v_sub_f32_e32 v5, v72, v73
	v_add_f32_e32 v1, v1, v3
	v_add_f32_e32 v1, v1, v5
	s_cbranch_scc0 .LBB0_178
	v_cmp_eq_u32_e32 vcc, 0, v20
	v_cmp_eq_u32_e64 s[0:1], v12, v2
	s_and_b64 s[4:5], s[0:1], vcc
	s_and_saveexec_b64 s[0:1], s[4:5]
	s_cbranch_execz .LBB0_181
	ds_read_b64 v[6:7], v13 offset:176
	v_lshl_or_b32 v4, v4, 4, v12
	v_ashrrev_i32_e32 v5, 31, v4
	s_waitcnt lgkmcnt(0)
	v_readfirstlane_b32 s4, v7
	v_readfirstlane_b32 s5, v6
	s_nop 0
	v_mov_b32_e32 v7, s4
	v_mov_b32_e32 v6, s5
	v_lshl_add_u64 v[4:5], v[4:5], 2, v[6:7]
	global_load_dword v3, v[4:5], off
	s_waitcnt vmcnt(0)
	v_add_f32_e32 v1, v1, v3
